# GEMM tile start: accumulators cleared with 64 v_mov_b64 instead of 128 v_mov_b32 (4 templates)
# baseline (speedup 1.0000x reference)
; template <class Epi, bool ALIGN_EPI, bool SP2>
; __device__ __forceinline__ void gemm_phase(LAS unsigned char* lds, const Gemm g, const StaticOrder& S, const Epi& E, const int tid) {
;     ...
; #pragma unroll
;         for (int a = 0; a < 2; ++a)
; #pragma unroll
;             for (int b = 0; b < 2; ++b)
; #pragma unroll
;                 for (int m = 0; m < 4; ++m)
; #pragma unroll
;                     for (int n = 0; n < 2; ++n) acc[a][b][m][n] = (f32x4){0.f, 0.f, 0.f, 0.f};
;         cur = nxt; cA = nA; cB = nB; ++ui;
.LBB0_310:
	s_add_u32 s0, s28, 0x80
	s_addc_u32 s1, s29, 0
	s_add_u32 s13, s18, 0x100
	s_addc_u32 s22, s19, 0
	s_mov_b32 s18, 0
	v_mov_b64_e32 v[0:1], 0
	v_mov_b64_e32 v[2:3], 0
	v_mov_b64_e32 v[4:5], 0
	v_mov_b64_e32 v[6:7], 0
	v_mov_b64_e32 v[8:9], 0
	v_mov_b64_e32 v[10:11], 0
	v_mov_b64_e32 v[12:13], 0
	v_mov_b64_e32 v[14:15], 0
	v_mov_b64_e32 v[16:17], 0
	v_mov_b64_e32 v[18:19], 0
	v_mov_b64_e32 v[20:21], 0
	v_mov_b64_e32 v[22:23], 0
	v_mov_b64_e32 v[24:25], 0
	v_mov_b64_e32 v[26:27], 0
	v_mov_b64_e32 v[28:29], 0
	v_mov_b64_e32 v[30:31], 0
	v_mov_b64_e32 v[32:33], 0
	v_mov_b64_e32 v[34:35], 0
	v_mov_b64_e32 v[36:37], 0
	v_mov_b64_e32 v[38:39], 0
	v_mov_b64_e32 v[40:41], 0
	v_mov_b64_e32 v[42:43], 0
	v_mov_b64_e32 v[44:45], 0
	v_mov_b64_e32 v[46:47], 0
	v_mov_b64_e32 v[48:49], 0
	v_mov_b64_e32 v[50:51], 0
	v_mov_b64_e32 v[52:53], 0
	v_mov_b64_e32 v[54:55], 0
	v_mov_b64_e32 v[56:57], 0
	v_mov_b64_e32 v[58:59], 0
	v_mov_b64_e32 v[60:61], 0
	v_mov_b64_e32 v[62:63], 0
	v_mov_b64_e32 v[64:65], 0
	v_mov_b64_e32 v[66:67], 0
	v_mov_b64_e32 v[68:69], 0
	v_mov_b64_e32 v[70:71], 0
	v_mov_b64_e32 v[72:73], 0
	v_mov_b64_e32 v[74:75], 0
	v_mov_b64_e32 v[76:77], 0
	v_mov_b64_e32 v[78:79], 0
	v_mov_b64_e32 v[80:81], 0
	v_mov_b64_e32 v[82:83], 0
	v_mov_b64_e32 v[84:85], 0
	v_mov_b64_e32 v[86:87], 0
	v_mov_b64_e32 v[88:89], 0
	v_mov_b64_e32 v[90:91], 0
	v_mov_b64_e32 v[92:93], 0
	v_mov_b64_e32 v[94:95], 0
	v_mov_b64_e32 v[96:97], 0
	v_mov_b64_e32 v[98:99], 0
	v_mov_b64_e32 v[100:101], 0
	v_mov_b64_e32 v[102:103], 0
	v_mov_b64_e32 v[104:105], 0
	v_mov_b64_e32 v[106:107], 0
	v_mov_b64_e32 v[108:109], 0
	v_mov_b64_e32 v[110:111], 0
	v_mov_b64_e32 v[112:113], 0
	v_mov_b64_e32 v[114:115], 0
	v_mov_b64_e32 v[116:117], 0
	v_mov_b64_e32 v[118:119], 0
	v_mov_b64_e32 v[120:121], 0
	v_mov_b64_e32 v[122:123], 0
	v_mov_b64_e32 v[124:125], 0
	v_mov_b64_e32 v[126:127], 0

; template <class Epi, bool ALIGN_EPI, bool SP2>
; __device__ __forceinline__ void gemm_phase(LAS unsigned char* lds, const Gemm g, const StaticOrder& S, const Epi& E, const int tid) {
;     ...
; #pragma unroll
;         for (int a = 0; a < 2; ++a)
; #pragma unroll
;             for (int b = 0; b < 2; ++b)
; #pragma unroll
;                 for (int m = 0; m < 4; ++m)
; #pragma unroll
;                     for (int n = 0; n < 2; ++n) acc[a][b][m][n] = (f32x4){0.f, 0.f, 0.f, 0.f};
;         cur = nxt; cA = nA; cB = nB; ++ui;
.LBB0_345:
	s_add_u32 s18, s18, 0x80
	s_addc_u32 s19, s19, 0
	s_add_u32 s13, s28, 0x100
	s_addc_u32 s26, s29, 0
	s_mov_b32 s27, 0
	v_mov_b64_e32 v[0:1], 0
	v_mov_b64_e32 v[2:3], 0
	v_mov_b64_e32 v[4:5], 0
	v_mov_b64_e32 v[6:7], 0
	v_mov_b64_e32 v[8:9], 0
	v_mov_b64_e32 v[10:11], 0
	v_mov_b64_e32 v[12:13], 0
	v_mov_b64_e32 v[14:15], 0
	v_mov_b64_e32 v[16:17], 0
	v_mov_b64_e32 v[18:19], 0
	v_mov_b64_e32 v[20:21], 0
	v_mov_b64_e32 v[22:23], 0
	v_mov_b64_e32 v[24:25], 0
	v_mov_b64_e32 v[26:27], 0
	v_mov_b64_e32 v[28:29], 0
	v_mov_b64_e32 v[30:31], 0
	v_mov_b64_e32 v[32:33], 0
	v_mov_b64_e32 v[34:35], 0
	v_mov_b64_e32 v[36:37], 0
	v_mov_b64_e32 v[38:39], 0
	v_mov_b64_e32 v[40:41], 0
	v_mov_b64_e32 v[42:43], 0
	v_mov_b64_e32 v[44:45], 0
	v_mov_b64_e32 v[46:47], 0
	v_mov_b64_e32 v[48:49], 0
	v_mov_b64_e32 v[50:51], 0
	v_mov_b64_e32 v[52:53], 0
	v_mov_b64_e32 v[54:55], 0
	v_mov_b64_e32 v[56:57], 0
	v_mov_b64_e32 v[58:59], 0
	v_mov_b64_e32 v[60:61], 0
	v_mov_b64_e32 v[62:63], 0
	v_mov_b64_e32 v[64:65], 0
	v_mov_b64_e32 v[66:67], 0
	v_mov_b64_e32 v[68:69], 0
	v_mov_b64_e32 v[70:71], 0
	v_mov_b64_e32 v[72:73], 0
	v_mov_b64_e32 v[74:75], 0
	v_mov_b64_e32 v[76:77], 0
	v_mov_b64_e32 v[78:79], 0
	v_mov_b64_e32 v[80:81], 0
	v_mov_b64_e32 v[82:83], 0
	v_mov_b64_e32 v[84:85], 0
	v_mov_b64_e32 v[86:87], 0
	v_mov_b64_e32 v[88:89], 0
	v_mov_b64_e32 v[90:91], 0
	v_mov_b64_e32 v[92:93], 0
	v_mov_b64_e32 v[94:95], 0
	v_mov_b64_e32 v[96:97], 0
	v_mov_b64_e32 v[98:99], 0
	v_mov_b64_e32 v[100:101], 0
	v_mov_b64_e32 v[102:103], 0
	v_mov_b64_e32 v[104:105], 0
	v_mov_b64_e32 v[106:107], 0
	v_mov_b64_e32 v[108:109], 0
	v_mov_b64_e32 v[110:111], 0
	v_mov_b64_e32 v[112:113], 0
	v_mov_b64_e32 v[114:115], 0
	v_mov_b64_e32 v[116:117], 0
	v_mov_b64_e32 v[118:119], 0
	v_mov_b64_e32 v[124:125], 0
	v_mov_b64_e32 v[126:127], 0
	v_mov_b64_e32 v[128:129], 0
	v_mov_b64_e32 v[130:131], 0

; template <class Epi, bool ALIGN_EPI, bool SP2>
; __device__ __forceinline__ void gemm_phase(LAS unsigned char* lds, const Gemm g, const StaticOrder& S, const Epi& E, const int tid) {
;     ...
; #pragma unroll
;         for (int a = 0; a < 2; ++a)
; #pragma unroll
;             for (int b = 0; b < 2; ++b)
; #pragma unroll
;                 for (int m = 0; m < 4; ++m)
; #pragma unroll
;                     for (int n = 0; n < 2; ++n) acc[a][b][m][n] = (f32x4){0.f, 0.f, 0.f, 0.f};
;         cur = nxt; cA = nA; cB = nB; ++ui;
.LBB0_397:
	s_add_u32 s0, s34, 0x80
	s_addc_u32 s1, s35, 0
	s_add_u32 s34, s28, 0x100
	s_addc_u32 s35, s29, 0
	s_mov_b32 s28, 0
	v_mov_b64_e32 v[0:1], 0
	v_mov_b64_e32 v[2:3], 0
	v_mov_b64_e32 v[4:5], 0
	v_mov_b64_e32 v[6:7], 0
	v_mov_b64_e32 v[8:9], 0
	v_mov_b64_e32 v[10:11], 0
	v_mov_b64_e32 v[12:13], 0
	v_mov_b64_e32 v[14:15], 0
	v_mov_b64_e32 v[16:17], 0
	v_mov_b64_e32 v[18:19], 0
	v_mov_b64_e32 v[20:21], 0
	v_mov_b64_e32 v[22:23], 0
	v_mov_b64_e32 v[24:25], 0
	v_mov_b64_e32 v[26:27], 0
	v_mov_b64_e32 v[28:29], 0
	v_mov_b64_e32 v[30:31], 0
	v_mov_b64_e32 v[32:33], 0
	v_mov_b64_e32 v[34:35], 0
	v_mov_b64_e32 v[36:37], 0
	v_mov_b64_e32 v[38:39], 0
	v_mov_b64_e32 v[40:41], 0
	v_mov_b64_e32 v[42:43], 0
	v_mov_b64_e32 v[44:45], 0
	v_mov_b64_e32 v[46:47], 0
	v_mov_b64_e32 v[48:49], 0
	v_mov_b64_e32 v[50:51], 0
	v_mov_b64_e32 v[52:53], 0
	v_mov_b64_e32 v[54:55], 0
	v_mov_b64_e32 v[56:57], 0
	v_mov_b64_e32 v[58:59], 0
	v_mov_b64_e32 v[60:61], 0
	v_mov_b64_e32 v[62:63], 0
	v_mov_b64_e32 v[64:65], 0
	v_mov_b64_e32 v[66:67], 0
	v_mov_b64_e32 v[68:69], 0
	v_mov_b64_e32 v[70:71], 0
	v_mov_b64_e32 v[72:73], 0
	v_mov_b64_e32 v[74:75], 0
	v_mov_b64_e32 v[76:77], 0
	v_mov_b64_e32 v[78:79], 0
	v_mov_b64_e32 v[80:81], 0
	v_mov_b64_e32 v[82:83], 0
	v_mov_b64_e32 v[84:85], 0
	v_mov_b64_e32 v[86:87], 0
	v_mov_b64_e32 v[88:89], 0
	v_mov_b64_e32 v[90:91], 0
	v_mov_b64_e32 v[92:93], 0
	v_mov_b64_e32 v[94:95], 0
	v_mov_b64_e32 v[96:97], 0
	v_mov_b64_e32 v[98:99], 0
	v_mov_b64_e32 v[100:101], 0
	v_mov_b64_e32 v[102:103], 0
	v_mov_b64_e32 v[108:109], 0
	v_mov_b64_e32 v[110:111], 0
	v_mov_b64_e32 v[112:113], 0
	v_mov_b64_e32 v[114:115], 0
	v_mov_b64_e32 v[116:117], 0
	v_mov_b64_e32 v[118:119], 0
	v_mov_b64_e32 v[120:121], 0
	v_mov_b64_e32 v[122:123], 0
	v_mov_b64_e32 v[124:125], 0
	v_mov_b64_e32 v[126:127], 0
	v_mov_b64_e32 v[128:129], 0
	v_mov_b64_e32 v[130:131], 0

; template <class Epi, bool ALIGN_EPI, bool SP2>
; __device__ __forceinline__ void gemm_phase(LAS unsigned char* lds, const Gemm g, const StaticOrder& S, const Epi& E, const int tid) {
;     ...
; #pragma unroll
;         for (int a = 0; a < 2; ++a)
; #pragma unroll
;             for (int b = 0; b < 2; ++b)
; #pragma unroll
;                 for (int m = 0; m < 4; ++m)
; #pragma unroll
;                     for (int n = 0; n < 2; ++n) acc[a][b][m][n] = (f32x4){0.f, 0.f, 0.f, 0.f};
;         cur = nxt; cA = nA; cB = nB; ++ui;
.LBB0_472:
	s_add_u32 s0, s44, 0x80
	s_addc_u32 s1, s45, 0
	s_add_u32 s44, s34, 0x100
	s_addc_u32 s45, s35, 0
	s_mov_b32 s34, 0
	v_mov_b64_e32 v[0:1], 0
	v_mov_b64_e32 v[2:3], 0
	v_mov_b64_e32 v[4:5], 0
	v_mov_b64_e32 v[6:7], 0
	v_mov_b64_e32 v[8:9], 0
	v_mov_b64_e32 v[10:11], 0
	v_mov_b64_e32 v[12:13], 0
	v_mov_b64_e32 v[14:15], 0
	v_mov_b64_e32 v[16:17], 0
	v_mov_b64_e32 v[18:19], 0
	v_mov_b64_e32 v[20:21], 0
	v_mov_b64_e32 v[22:23], 0
	v_mov_b64_e32 v[24:25], 0
	v_mov_b64_e32 v[26:27], 0
	v_mov_b64_e32 v[28:29], 0
	v_mov_b64_e32 v[30:31], 0
	v_mov_b64_e32 v[32:33], 0
	v_mov_b64_e32 v[34:35], 0
	v_mov_b64_e32 v[36:37], 0
	v_mov_b64_e32 v[38:39], 0
	v_mov_b64_e32 v[40:41], 0
	v_mov_b64_e32 v[42:43], 0
	v_mov_b64_e32 v[44:45], 0
	v_mov_b64_e32 v[46:47], 0
	v_mov_b64_e32 v[48:49], 0
	v_mov_b64_e32 v[50:51], 0
	v_mov_b64_e32 v[52:53], 0
	v_mov_b64_e32 v[54:55], 0
	v_mov_b64_e32 v[56:57], 0
	v_mov_b64_e32 v[58:59], 0
	v_mov_b64_e32 v[60:61], 0
	v_mov_b64_e32 v[62:63], 0
	v_mov_b64_e32 v[64:65], 0
	v_mov_b64_e32 v[66:67], 0
	v_mov_b64_e32 v[68:69], 0
	v_mov_b64_e32 v[70:71], 0
	v_mov_b64_e32 v[72:73], 0
	v_mov_b64_e32 v[74:75], 0
	v_mov_b64_e32 v[76:77], 0
	v_mov_b64_e32 v[78:79], 0
	v_mov_b64_e32 v[80:81], 0
	v_mov_b64_e32 v[82:83], 0
	v_mov_b64_e32 v[84:85], 0
	v_mov_b64_e32 v[86:87], 0
	v_mov_b64_e32 v[88:89], 0
	v_mov_b64_e32 v[90:91], 0
	v_mov_b64_e32 v[92:93], 0
	v_mov_b64_e32 v[94:95], 0
	v_mov_b64_e32 v[96:97], 0
	v_mov_b64_e32 v[98:99], 0
	v_mov_b64_e32 v[100:101], 0
	v_mov_b64_e32 v[102:103], 0
	v_mov_b64_e32 v[104:105], 0
	v_mov_b64_e32 v[106:107], 0
	v_mov_b64_e32 v[108:109], 0
	v_mov_b64_e32 v[110:111], 0
	v_mov_b64_e32 v[112:113], 0
	v_mov_b64_e32 v[114:115], 0
	v_mov_b64_e32 v[116:117], 0
	v_mov_b64_e32 v[118:119], 0
	v_mov_b64_e32 v[128:129], 0
	v_mov_b64_e32 v[130:131], 0
	v_mov_b64_e32 v[132:133], 0
	v_mov_b64_e32 v[134:135], 0
